# K-loop heads aligned to 64 bytes
# speedup vs baseline: 1.0016x; 1.0016x over previous
.LBB0_179:
	s_add_u32 s0, s0, 0x40080
	s_addc_u32 s1, s1, 0
	s_add_u32 s53, s4, 0x100
	v_mov_b32_e32 v0, 0
	s_addc_u32 s79, s5, 0
	s_mov_b32 vcc_lo, -2
	v_mov_b32_e32 v1, v0
	v_mov_b32_e32 v2, v0
	v_mov_b32_e32 v3, v0
	v_mov_b32_e32 v4, v0
	v_mov_b32_e32 v5, v0
	v_mov_b32_e32 v6, v0
	v_mov_b32_e32 v7, v0
	v_mov_b32_e32 v16, v0
	v_mov_b32_e32 v17, v0
	v_mov_b32_e32 v18, v0
	v_mov_b32_e32 v19, v0
	v_mov_b32_e32 v20, v0
	v_mov_b32_e32 v21, v0
	v_mov_b32_e32 v22, v0
	v_mov_b32_e32 v23, v0
	v_mov_b32_e32 v32, v0
	v_mov_b32_e32 v33, v0
	v_mov_b32_e32 v34, v0
	v_mov_b32_e32 v35, v0
	v_mov_b32_e32 v36, v0
	v_mov_b32_e32 v37, v0
	v_mov_b32_e32 v38, v0
	v_mov_b32_e32 v39, v0
	v_mov_b32_e32 v48, v0
	v_mov_b32_e32 v49, v0
	v_mov_b32_e32 v50, v0
	v_mov_b32_e32 v51, v0
	v_mov_b32_e32 v52, v0
	v_mov_b32_e32 v53, v0
	v_mov_b32_e32 v54, v0
	v_mov_b32_e32 v55, v0
	v_mov_b32_e32 v8, v0
	v_mov_b32_e32 v9, v0
	v_mov_b32_e32 v10, v0
	v_mov_b32_e32 v11, v0
	v_mov_b32_e32 v12, v0
	v_mov_b32_e32 v13, v0
	v_mov_b32_e32 v14, v0
	v_mov_b32_e32 v15, v0
	v_mov_b32_e32 v24, v0
	v_mov_b32_e32 v25, v0
	v_mov_b32_e32 v26, v0
	v_mov_b32_e32 v27, v0
	v_mov_b32_e32 v28, v0
	v_mov_b32_e32 v29, v0
	v_mov_b32_e32 v30, v0
	v_mov_b32_e32 v31, v0
	v_mov_b32_e32 v40, v0
	v_mov_b32_e32 v41, v0
	v_mov_b32_e32 v42, v0
	v_mov_b32_e32 v43, v0
	v_mov_b32_e32 v44, v0
	v_mov_b32_e32 v45, v0
	v_mov_b32_e32 v46, v0
	v_mov_b32_e32 v47, v0
	v_mov_b32_e32 v56, v0
	v_mov_b32_e32 v57, v0
	v_mov_b32_e32 v58, v0
	v_mov_b32_e32 v59, v0
	v_mov_b32_e32 v60, v0
	v_mov_b32_e32 v61, v0
	v_mov_b32_e32 v62, v0
	v_mov_b32_e32 v63, v0
	v_mov_b32_e32 v64, v0
	v_mov_b32_e32 v65, v0
	v_mov_b32_e32 v66, v0
	v_mov_b32_e32 v67, v0
	v_mov_b32_e32 v68, v0
	v_mov_b32_e32 v69, v0
	v_mov_b32_e32 v70, v0
	v_mov_b32_e32 v71, v0
	v_mov_b32_e32 v80, v0
	v_mov_b32_e32 v81, v0
	v_mov_b32_e32 v82, v0
	v_mov_b32_e32 v83, v0
	v_mov_b32_e32 v84, v0
	v_mov_b32_e32 v85, v0
	v_mov_b32_e32 v86, v0
	v_mov_b32_e32 v87, v0
	v_mov_b32_e32 v96, v0
	v_mov_b32_e32 v97, v0
	v_mov_b32_e32 v98, v0
	v_mov_b32_e32 v99, v0
	v_mov_b32_e32 v100, v0
	v_mov_b32_e32 v101, v0
	v_mov_b32_e32 v102, v0
	v_mov_b32_e32 v103, v0
	v_mov_b32_e32 v112, v0
	v_mov_b32_e32 v113, v0
	v_mov_b32_e32 v114, v0
	v_mov_b32_e32 v115, v0
	v_mov_b32_e32 v116, v0
	v_mov_b32_e32 v117, v0
	v_mov_b32_e32 v118, v0
	v_mov_b32_e32 v119, v0
	v_mov_b32_e32 v72, v0
	v_mov_b32_e32 v73, v0
	v_mov_b32_e32 v74, v0
	v_mov_b32_e32 v75, v0
	v_mov_b32_e32 v76, v0
	v_mov_b32_e32 v77, v0
	v_mov_b32_e32 v78, v0
	v_mov_b32_e32 v79, v0
	v_mov_b32_e32 v88, v0
	v_mov_b32_e32 v89, v0
	v_mov_b32_e32 v90, v0
	v_mov_b32_e32 v91, v0
	v_mov_b32_e32 v92, v0
	v_mov_b32_e32 v93, v0
	v_mov_b32_e32 v94, v0
	v_mov_b32_e32 v95, v0
	v_mov_b32_e32 v104, v0
	v_mov_b32_e32 v105, v0
	v_mov_b32_e32 v106, v0
	v_mov_b32_e32 v107, v0
	v_mov_b32_e32 v108, v0
	v_mov_b32_e32 v109, v0
	v_mov_b32_e32 v110, v0
	v_mov_b32_e32 v111, v0
	v_mov_b32_e32 v120, v0
	v_mov_b32_e32 v121, v0
	v_mov_b32_e32 v122, v0
	v_mov_b32_e32 v123, v0
	v_mov_b32_e32 v124, v0
	v_mov_b32_e32 v125, v0
	v_mov_b32_e32 v126, v0
	v_mov_b32_e32 v127, v0
	.p2align	6

.LBB0_305:
	s_ashr_i32 s89, s88, 31
	s_lshl_b64 s[16:17], s[88:89], 19
	s_add_u32 s90, s80, s16
	s_addc_u32 s91, s81, s17
	s_ashr_i32 s87, s86, 31
	s_lshl_b64 s[16:17], s[86:87], 19
	s_add_u32 s92, s39, s16
	s_addc_u32 s93, s49, s17
	s_and_b64 s[16:17], s[6:7], exec
	s_cselect_b32 s11, s91, s9
	s_cselect_b32 s87, s90, s8
	s_cselect_b32 s89, s93, s41
	s_cselect_b32 s95, s92, s40
	s_add_u32 s8, s8, 0x40080
	s_addc_u32 s9, s9, 0
	s_add_u32 vcc_lo, s40, 0x100
	v_mov_b32_e32 v0, 0
	s_addc_u32 vcc_hi, s41, 0
	s_mov_b32 s16, -2
	v_mov_b32_e32 v1, v0
	v_mov_b32_e32 v2, v0
	v_mov_b32_e32 v3, v0
	v_mov_b32_e32 v8, v0
	v_mov_b32_e32 v9, v0
	v_mov_b32_e32 v10, v0
	v_mov_b32_e32 v11, v0
	v_mov_b32_e32 v16, v0
	v_mov_b32_e32 v17, v0
	v_mov_b32_e32 v18, v0
	v_mov_b32_e32 v19, v0
	v_mov_b32_e32 v24, v0
	v_mov_b32_e32 v25, v0
	v_mov_b32_e32 v26, v0
	v_mov_b32_e32 v27, v0
	v_mov_b32_e32 v32, v0
	v_mov_b32_e32 v33, v0
	v_mov_b32_e32 v34, v0
	v_mov_b32_e32 v35, v0
	v_mov_b32_e32 v40, v0
	v_mov_b32_e32 v41, v0
	v_mov_b32_e32 v42, v0
	v_mov_b32_e32 v43, v0
	v_mov_b32_e32 v48, v0
	v_mov_b32_e32 v49, v0
	v_mov_b32_e32 v50, v0
	v_mov_b32_e32 v51, v0
	v_mov_b32_e32 v56, v0
	v_mov_b32_e32 v57, v0
	v_mov_b32_e32 v58, v0
	v_mov_b32_e32 v59, v0
	v_mov_b32_e32 v4, v0
	v_mov_b32_e32 v5, v0
	v_mov_b32_e32 v6, v0
	v_mov_b32_e32 v7, v0
	v_mov_b32_e32 v12, v0
	v_mov_b32_e32 v13, v0
	v_mov_b32_e32 v14, v0
	v_mov_b32_e32 v15, v0
	v_mov_b32_e32 v20, v0
	v_mov_b32_e32 v21, v0
	v_mov_b32_e32 v22, v0
	v_mov_b32_e32 v23, v0
	v_mov_b32_e32 v28, v0
	v_mov_b32_e32 v29, v0
	v_mov_b32_e32 v30, v0
	v_mov_b32_e32 v31, v0
	v_mov_b32_e32 v36, v0
	v_mov_b32_e32 v37, v0
	v_mov_b32_e32 v38, v0
	v_mov_b32_e32 v39, v0
	v_mov_b32_e32 v44, v0
	v_mov_b32_e32 v45, v0
	v_mov_b32_e32 v46, v0
	v_mov_b32_e32 v47, v0
	v_mov_b32_e32 v52, v0
	v_mov_b32_e32 v53, v0
	v_mov_b32_e32 v54, v0
	v_mov_b32_e32 v55, v0
	v_mov_b32_e32 v60, v0
	v_mov_b32_e32 v61, v0
	v_mov_b32_e32 v62, v0
	v_mov_b32_e32 v63, v0
	v_mov_b32_e32 v64, v0
	v_mov_b32_e32 v65, v0
	v_mov_b32_e32 v66, v0
	v_mov_b32_e32 v67, v0
	v_mov_b32_e32 v72, v0
	v_mov_b32_e32 v73, v0
	v_mov_b32_e32 v74, v0
	v_mov_b32_e32 v75, v0
	v_mov_b32_e32 v80, v0
	v_mov_b32_e32 v81, v0
	v_mov_b32_e32 v82, v0
	v_mov_b32_e32 v83, v0
	v_mov_b32_e32 v88, v0
	v_mov_b32_e32 v89, v0
	v_mov_b32_e32 v90, v0
	v_mov_b32_e32 v91, v0
	v_mov_b32_e32 v96, v0
	v_mov_b32_e32 v97, v0
	v_mov_b32_e32 v98, v0
	v_mov_b32_e32 v99, v0
	v_mov_b32_e32 v104, v0
	v_mov_b32_e32 v105, v0
	v_mov_b32_e32 v106, v0
	v_mov_b32_e32 v107, v0
	v_mov_b32_e32 v120, v0
	v_mov_b32_e32 v121, v0
	v_mov_b32_e32 v122, v0
	v_mov_b32_e32 v123, v0
	v_mov_b32_e32 v128, v0
	v_mov_b32_e32 v129, v0
	v_mov_b32_e32 v130, v0
	v_mov_b32_e32 v131, v0
	v_mov_b32_e32 v68, v0
	v_mov_b32_e32 v69, v0
	v_mov_b32_e32 v70, v0
	v_mov_b32_e32 v71, v0
	v_mov_b32_e32 v76, v0
	v_mov_b32_e32 v77, v0
	v_mov_b32_e32 v78, v0
	v_mov_b32_e32 v79, v0
	v_mov_b32_e32 v84, v0
	v_mov_b32_e32 v85, v0
	v_mov_b32_e32 v86, v0
	v_mov_b32_e32 v87, v0
	v_mov_b32_e32 v92, v0
	v_mov_b32_e32 v93, v0
	v_mov_b32_e32 v94, v0
	v_mov_b32_e32 v95, v0
	v_mov_b32_e32 v100, v0
	v_mov_b32_e32 v101, v0
	v_mov_b32_e32 v102, v0
	v_mov_b32_e32 v103, v0
	v_mov_b32_e32 v108, v0
	v_mov_b32_e32 v109, v0
	v_mov_b32_e32 v110, v0
	v_mov_b32_e32 v111, v0
	v_mov_b32_e32 v124, v0
	v_mov_b32_e32 v125, v0
	v_mov_b32_e32 v126, v0
	v_mov_b32_e32 v127, v0
	v_mov_b32_e32 v132, v0
	v_mov_b32_e32 v133, v0
	v_mov_b32_e32 v134, v0
	v_mov_b32_e32 v135, v0
	.p2align	6

.LBB0_494:
	s_add_u32 s27, s30, 0x100
	s_addc_u32 s55, s31, 0
	s_ashr_i32 s23, s22, 31
	s_lshl_b64 s[24:25], s[22:23], 20
	s_add_u32 s28, s12, s24
	s_addc_u32 s29, s13, s25
	s_ashr_i32 s21, s20, 31
	s_lshl_b64 s[24:25], s[20:21], 20
	s_add_u32 s24, s88, s24
	s_addc_u32 s25, s89, s25
	s_and_b64 s[34:35], s[4:5], exec
	s_cselect_b32 s21, s29, s17
	s_cselect_b32 s23, s28, s16
	s_cselect_b32 s56, s25, s31
	s_cselect_b32 s57, s24, s30
	v_lshl_add_u64 v[140:141], s[16:17], 0, v[132:133]
	v_lshl_add_u64 v[142:143], s[16:17], 0, v[134:135]
	s_mov_b32 s58, -2
	s_mov_b64 s[30:31], 0
	.p2align	6
